# attention fast path now on both units (next-tile loads in QK gaps, LDS writes in PV gaps, 6-deep LDS fragment ring)
# baseline (speedup 1.0000x reference)
.LaF1_fast:
	s_waitcnt vmcnt(0)
	s_bitcmp1_b32 s51, 0
	s_cselect_b32 s53, 0, 0xac00
	s_setprio 1
	v_add_u32_e32 v253, s53, v171
	v_add_u32_e32 v252, s53, v181
	ds_read_b128 v[196:199], v253
	ds_read_b128 v[200:203], v253 offset:12800
	ds_read_b128 v[204:207], v253 offset:32
	ds_read_b128 v[208:211], v253 offset:12832
	ds_read_b128 v[212:215], v253 offset:64
	ds_read_b128 v[216:219], v253 offset:12864
	s_waitcnt lgkmcnt(5)
	v_mfma_f32_32x32x16_bf16 v[66:81], v[196:199], v[110:113], 0
	ds_read_b128 v[220:223], v253 offset:96
	v_lshl_add_u64 v[244:245], s[2:3], 0, v[176:177]
	s_waitcnt lgkmcnt(5)
	v_mfma_f32_32x32x16_bf16 v[82:97], v[200:203], v[110:113], 0
	ds_read_b128 v[224:227], v253 offset:12896
	v_add_co_u32_e32 v246, vcc, 0x16020000, v244
	s_waitcnt lgkmcnt(5)
	v_mfma_f32_32x32x16_bf16 v[66:81], v[204:207], v[118:121], v[66:81]
	ds_read_b128 v[228:231], v253 offset:128
	s_nop 1
	s_waitcnt lgkmcnt(5)
	v_mfma_f32_32x32x16_bf16 v[82:97], v[208:211], v[118:121], v[82:97]
	ds_read_b128 v[232:235], v253 offset:12928
	v_addc_co_u32_e32 v247, vcc, 0, v245, vcc
	s_waitcnt lgkmcnt(5)
	v_mfma_f32_32x32x16_bf16 v[66:81], v[212:215], v[122:125], v[66:81]
	ds_read_b128 v[236:239], v253 offset:160
	v_add_co_u32_e32 v244, vcc, 0x16030000, v244
	s_waitcnt lgkmcnt(5)
	v_mfma_f32_32x32x16_bf16 v[82:97], v[216:219], v[122:125], v[82:97]
	ds_read_b128 v[240:243], v253 offset:12960
	s_nop 1
	s_waitcnt lgkmcnt(5)
	v_mfma_f32_32x32x16_bf16 v[66:81], v[220:223], v[126:129], v[66:81]
	ds_read_b128 v[196:199], v253 offset:192
	v_addc_co_u32_e32 v245, vcc, 0, v245, vcc
	s_waitcnt lgkmcnt(5)
	v_mfma_f32_32x32x16_bf16 v[82:97], v[224:227], v[126:129], v[82:97]
	ds_read_b128 v[200:203], v253 offset:12992
	global_load_dwordx4 v[98:101], v[246:247], off
	s_waitcnt lgkmcnt(5)
	v_mfma_f32_32x32x16_bf16 v[66:81], v[228:231], v[130:133], v[66:81]
	ds_read_b128 v[204:207], v253 offset:224
	global_load_dwordx4 v[102:105], v[244:245], off
	s_waitcnt lgkmcnt(5)
	v_mfma_f32_32x32x16_bf16 v[82:97], v[232:235], v[130:133], v[82:97]
	ds_read_b128 v[208:211], v253 offset:13024
	v_lshl_add_u64 v[246:247], s[2:3], 0, v[178:179]
	s_waitcnt lgkmcnt(5)
	v_mfma_f32_32x32x16_bf16 v[66:81], v[236:239], v[134:137], v[66:81]
	ds_read_b128 v[212:215], v253 offset:256
	v_add_co_u32_e32 v248, vcc, 0x1a000000, v246
	s_waitcnt lgkmcnt(5)
	v_mfma_f32_32x32x16_bf16 v[82:97], v[240:243], v[134:137], v[82:97]
	ds_read_b128 v[216:219], v253 offset:13056
	v_lshl_add_u64 v[244:245], s[2:3], 0, v[174:175]
	s_waitcnt lgkmcnt(5)
	v_mfma_f32_32x32x16_bf16 v[66:81], v[196:199], v[138:141], v[66:81]
	ds_read_b128 v[220:223], v253 offset:288
	s_nop 0
	s_waitcnt lgkmcnt(5)
	v_mfma_f32_32x32x16_bf16 v[82:97], v[200:203], v[138:141], v[82:97]
	ds_read_b128 v[224:227], v253 offset:13088
	v_addc_co_u32_e32 v249, vcc, 0, v247, vcc
	s_waitcnt lgkmcnt(5)
	v_mfma_f32_32x32x16_bf16 v[66:81], v[204:207], v[142:145], v[66:81]
	ds_read_b128 v[228:231], v253 offset:320
	global_load_dwordx4 v[106:109], v[244:245], off
	s_waitcnt lgkmcnt(5)
	v_mfma_f32_32x32x16_bf16 v[82:97], v[208:211], v[142:145], v[82:97]
	ds_read_b128 v[232:235], v253 offset:13120
	global_load_dwordx4 v[114:117], v[248:249], off offset:128
	s_waitcnt lgkmcnt(5)
	v_mfma_f32_32x32x16_bf16 v[66:81], v[212:215], v[150:153], v[66:81]
	ds_read_b128 v[236:239], v253 offset:352
	v_add_co_u32_e32 v244, vcc, 0x1a400000, v246
	s_waitcnt lgkmcnt(5)
	v_mfma_f32_32x32x16_bf16 v[82:97], v[216:219], v[150:153], v[82:97]
	ds_read_b128 v[240:243], v253 offset:13152
	s_nop 1
	s_waitcnt lgkmcnt(5)
	v_mfma_f32_32x32x16_bf16 v[66:81], v[220:223], v[154:157], v[66:81]
	v_addc_co_u32_e32 v245, vcc, 0, v247, vcc
	s_waitcnt lgkmcnt(4)
	v_mfma_f32_32x32x16_bf16 v[82:97], v[224:227], v[154:157], v[82:97]
	global_load_dwordx4 v[146:149], v[244:245], off offset:128
	s_waitcnt lgkmcnt(3)
	v_mfma_f32_32x32x16_bf16 v[66:81], v[228:231], v[158:161], v[66:81]
	s_waitcnt lgkmcnt(2)
	v_mfma_f32_32x32x16_bf16 v[82:97], v[232:235], v[158:161], v[82:97]
	s_waitcnt lgkmcnt(1)
	v_mfma_f32_32x32x16_bf16 v[66:81], v[236:239], v[162:165], v[66:81]
	s_waitcnt lgkmcnt(0)
	v_mfma_f32_32x32x16_bf16 v[82:97], v[240:243], v[162:165], v[82:97]
	ds_read_b128 v[196:199], v252 offset:25600
	ds_read_b128 v[200:203], v252 offset:25632
	ds_read_b128 v[204:207], v252 offset:25664
	ds_read_b128 v[208:211], v252 offset:25696
	ds_read_b128 v[212:215], v252 offset:30208
	ds_read_b128 v[216:219], v252 offset:30240
	s_setprio 0
	s_add_i32 s54, s52, 63
	s_cmp_le_i32 s54, s47
	s_cbranch_scc1 .LaF1_1
	v_add_u32_e32 v0, s52, v168
	v_add_u32_e32 v184, 32, v0
	v_cmp_le_i32_e32 vcc, v184, v173
	v_add_u32_e32 v184, 33, v0
	s_nop 3
	v_cndmask_b32_e32 v82, v180, v82, vcc
	v_cmp_lt_i32_e32 vcc, v0, v173
	s_nop 1
	v_cndmask_b32_e32 v67, v180, v67, vcc
	v_cmp_le_i32_e32 vcc, v0, v173
	s_nop 1
	v_cndmask_b32_e32 v66, v180, v66, vcc
	v_cmp_le_i32_e32 vcc, v184, v173
	v_add_u32_e32 v184, 2, v0
	s_nop 0
	v_cndmask_b32_e32 v83, v180, v83, vcc
	v_cmp_le_i32_e32 vcc, v184, v173
	v_add_u32_e32 v184, 34, v0
	s_nop 0
	v_cndmask_b32_e32 v68, v180, v68, vcc
	v_cmp_le_i32_e32 vcc, v184, v173
	v_add_u32_e32 v184, 3, v0
	s_nop 0
	v_cndmask_b32_e32 v84, v180, v84, vcc
	v_cmp_le_i32_e32 vcc, v184, v173
	v_add_u32_e32 v184, 35, v0
	s_nop 0
	v_cndmask_b32_e32 v69, v180, v69, vcc
	v_cmp_le_i32_e32 vcc, v184, v173
	v_add_u32_e32 v184, 4, v0
	s_nop 0
	v_cndmask_b32_e32 v85, v180, v85, vcc
	v_cmp_le_i32_e32 vcc, v184, v173
	v_add_u32_e32 v184, 36, v0
	s_nop 0
	v_cndmask_b32_e32 v70, v180, v70, vcc
	v_cmp_le_i32_e32 vcc, v184, v173
	v_add_u32_e32 v184, 5, v0
	s_nop 0
	v_cndmask_b32_e32 v86, v180, v86, vcc
	v_cmp_le_i32_e32 vcc, v184, v173
	v_add_u32_e32 v184, 37, v0
	s_nop 0
	v_cndmask_b32_e32 v71, v180, v71, vcc
	v_cmp_le_i32_e32 vcc, v184, v173
	v_add_u32_e32 v184, 6, v0
	s_nop 0
	v_cndmask_b32_e32 v87, v180, v87, vcc
	v_cmp_le_i32_e32 vcc, v184, v173
	v_add_u32_e32 v184, 38, v0
	s_nop 0
	v_cndmask_b32_e32 v72, v180, v72, vcc
	v_cmp_le_i32_e32 vcc, v184, v173
	v_add_u32_e32 v184, 7, v0
	s_nop 0
	v_cndmask_b32_e32 v88, v180, v88, vcc
	v_cmp_le_i32_e32 vcc, v184, v173
	v_add_u32_e32 v184, 39, v0
	s_nop 0
	v_cndmask_b32_e32 v73, v180, v73, vcc
	v_cmp_le_i32_e32 vcc, v184, v173
	v_add_u32_e32 v184, 16, v0
	s_nop 0
	v_cndmask_b32_e32 v89, v180, v89, vcc
	v_cmp_le_i32_e32 vcc, v184, v173
	v_add_u32_e32 v184, 48, v0
	s_nop 0
	v_cndmask_b32_e32 v74, v180, v74, vcc
	v_cmp_le_i32_e32 vcc, v184, v173
	v_add_u32_e32 v184, 17, v0
	s_nop 0
	v_cndmask_b32_e32 v90, v180, v90, vcc
	v_cmp_le_i32_e32 vcc, v184, v173
	v_add_u32_e32 v184, 49, v0
	s_nop 0
	v_cndmask_b32_e32 v75, v180, v75, vcc
	v_cmp_le_i32_e32 vcc, v184, v173
	v_add_u32_e32 v184, 18, v0
	s_nop 0
	v_cndmask_b32_e32 v91, v180, v91, vcc
	v_cmp_le_i32_e32 vcc, v184, v173
	v_add_u32_e32 v184, 50, v0
	s_nop 0
	v_cndmask_b32_e32 v76, v180, v76, vcc
	v_cmp_le_i32_e32 vcc, v184, v173
	v_add_u32_e32 v184, 19, v0
	s_nop 0
	v_cndmask_b32_e32 v92, v180, v92, vcc
	v_cmp_le_i32_e32 vcc, v184, v173
	v_add_u32_e32 v184, 51, v0
	s_nop 0
	v_cndmask_b32_e32 v77, v180, v77, vcc
	v_cmp_le_i32_e32 vcc, v184, v173
	v_add_u32_e32 v184, 20, v0
	s_nop 0
	v_cndmask_b32_e32 v93, v180, v93, vcc
	v_cmp_le_i32_e32 vcc, v184, v173
	v_add_u32_e32 v184, 52, v0
	s_nop 0
	v_cndmask_b32_e32 v78, v180, v78, vcc
	v_cmp_le_i32_e32 vcc, v184, v173
	v_add_u32_e32 v184, 21, v0
	s_nop 0
	v_cndmask_b32_e32 v94, v180, v94, vcc
	v_cmp_le_i32_e32 vcc, v184, v173
	v_add_u32_e32 v184, 53, v0
	s_nop 0
	v_cndmask_b32_e32 v79, v180, v79, vcc
	v_cmp_le_i32_e32 vcc, v184, v173
	v_add_u32_e32 v184, 22, v0
	s_nop 0
	v_cndmask_b32_e32 v95, v180, v95, vcc
	v_cmp_le_i32_e32 vcc, v184, v173
	v_add_u32_e32 v184, 54, v0
	s_nop 0
	v_cndmask_b32_e32 v80, v180, v80, vcc
	v_cmp_le_i32_e32 vcc, v184, v173
	v_add_u32_e32 v184, 23, v0
	v_add_u32_e32 v0, 55, v0
	v_cndmask_b32_e32 v96, v180, v96, vcc
	v_cmp_le_i32_e32 vcc, v184, v173
	s_nop 1
	v_cndmask_b32_e32 v81, v180, v81, vcc
	v_cmp_le_i32_e32 vcc, v0, v173
	s_nop 1
	v_cndmask_b32_e32 v97, v180, v97, vcc

.LBB0_1491:
	s_cmp_lt_u32 s36, s46
	s_cselect_b64 s[24:25], -1, 0
	s_cmp_ge_u32 s36, s46
	s_cbranch_scc1 .LBB0_1494
	s_cmp_gt_i32 s37, s47
	s_cbranch_scc0 .LaF2_fast
	v_lshl_add_u64 v[66:67], s[2:3], 0, v[176:177]
	v_add_co_u32_e32 v68, vcc, 0x16020000, v66
	s_nop 1
	v_addc_co_u32_e32 v69, vcc, 0, v67, vcc
	v_add_co_u32_e32 v66, vcc, 0x16030000, v66
	s_nop 1
	v_addc_co_u32_e32 v67, vcc, 0, v67, vcc
	global_load_dwordx4 v[98:101], v[68:69], off
	global_load_dwordx4 v[102:105], v[66:67], off
	v_lshl_add_u64 v[68:69], s[2:3], 0, v[178:179]
	v_add_co_u32_e32 v70, vcc, 0x1a000000, v68
	v_lshl_add_u64 v[66:67], s[2:3], 0, v[174:175]
	s_nop 0
	v_addc_co_u32_e32 v71, vcc, 0, v69, vcc
	global_load_dwordx4 v[106:109], v[66:67], off
	global_load_dwordx4 v[126:129], v[70:71], off offset:128
	v_add_co_u32_e32 v66, vcc, 0x1a400000, v68
	s_nop 1
	v_addc_co_u32_e32 v67, vcc, 0, v69, vcc
	global_load_dwordx4 v[150:153], v[66:67], off offset:128
	s_cmp_gt_i32 s37, s47
	s_cbranch_scc0 .LBB0_1495

.LaF2_fast:
	s_waitcnt vmcnt(0)
	s_bitcmp1_b32 s36, 0
	s_cselect_b32 s4, 0, 0xac00
	s_setprio 1
	v_add_u32_e32 v253, s4, v171
	v_add_u32_e32 v252, s4, v181
	ds_read_b128 v[196:199], v253
	ds_read_b128 v[200:203], v253 offset:12800
	ds_read_b128 v[204:207], v253 offset:32
	ds_read_b128 v[208:211], v253 offset:12832
	ds_read_b128 v[212:215], v253 offset:64
	ds_read_b128 v[216:219], v253 offset:12864
	s_waitcnt lgkmcnt(5)
	v_mfma_f32_32x32x16_bf16 v[66:81], v[196:199], v[110:113], 0
	ds_read_b128 v[220:223], v253 offset:96
	v_lshl_add_u64 v[244:245], s[2:3], 0, v[176:177]
	s_waitcnt lgkmcnt(5)
	v_mfma_f32_32x32x16_bf16 v[82:97], v[200:203], v[110:113], 0
	ds_read_b128 v[224:227], v253 offset:12896
	v_add_co_u32_e32 v246, vcc, 0x16020000, v244
	s_waitcnt lgkmcnt(5)
	v_mfma_f32_32x32x16_bf16 v[66:81], v[204:207], v[114:117], v[66:81]
	ds_read_b128 v[228:231], v253 offset:128
	s_nop 1
	s_waitcnt lgkmcnt(5)
	v_mfma_f32_32x32x16_bf16 v[82:97], v[208:211], v[114:117], v[82:97]
	ds_read_b128 v[232:235], v253 offset:12928
	v_addc_co_u32_e32 v247, vcc, 0, v245, vcc
	s_waitcnt lgkmcnt(5)
	v_mfma_f32_32x32x16_bf16 v[66:81], v[212:215], v[118:121], v[66:81]
	ds_read_b128 v[236:239], v253 offset:160
	v_add_co_u32_e32 v244, vcc, 0x16030000, v244
	s_waitcnt lgkmcnt(5)
	v_mfma_f32_32x32x16_bf16 v[82:97], v[216:219], v[118:121], v[82:97]
	ds_read_b128 v[240:243], v253 offset:12960
	s_nop 1
	s_waitcnt lgkmcnt(5)
	v_mfma_f32_32x32x16_bf16 v[66:81], v[220:223], v[122:125], v[66:81]
	ds_read_b128 v[196:199], v253 offset:192
	v_addc_co_u32_e32 v245, vcc, 0, v245, vcc
	s_waitcnt lgkmcnt(5)
	v_mfma_f32_32x32x16_bf16 v[82:97], v[224:227], v[122:125], v[82:97]
	ds_read_b128 v[200:203], v253 offset:12992
	global_load_dwordx4 v[98:101], v[246:247], off
	s_waitcnt lgkmcnt(5)
	v_mfma_f32_32x32x16_bf16 v[66:81], v[228:231], v[130:133], v[66:81]
	ds_read_b128 v[204:207], v253 offset:224
	global_load_dwordx4 v[102:105], v[244:245], off
	s_waitcnt lgkmcnt(5)
	v_mfma_f32_32x32x16_bf16 v[82:97], v[232:235], v[130:133], v[82:97]
	ds_read_b128 v[208:211], v253 offset:13024
	v_lshl_add_u64 v[246:247], s[2:3], 0, v[178:179]
	s_waitcnt lgkmcnt(5)
	v_mfma_f32_32x32x16_bf16 v[66:81], v[236:239], v[134:137], v[66:81]
	ds_read_b128 v[212:215], v253 offset:256
	v_add_co_u32_e32 v248, vcc, 0x1a000000, v246
	s_waitcnt lgkmcnt(5)
	v_mfma_f32_32x32x16_bf16 v[82:97], v[240:243], v[134:137], v[82:97]
	ds_read_b128 v[216:219], v253 offset:13056
	v_lshl_add_u64 v[244:245], s[2:3], 0, v[174:175]
	s_waitcnt lgkmcnt(5)
	v_mfma_f32_32x32x16_bf16 v[66:81], v[196:199], v[138:141], v[66:81]
	ds_read_b128 v[220:223], v253 offset:288
	s_nop 0
	s_waitcnt lgkmcnt(5)
	v_mfma_f32_32x32x16_bf16 v[82:97], v[200:203], v[138:141], v[82:97]
	ds_read_b128 v[224:227], v253 offset:13088
	v_addc_co_u32_e32 v249, vcc, 0, v247, vcc
	s_waitcnt lgkmcnt(5)
	v_mfma_f32_32x32x16_bf16 v[66:81], v[204:207], v[142:145], v[66:81]
	ds_read_b128 v[228:231], v253 offset:320
	global_load_dwordx4 v[106:109], v[244:245], off
	s_waitcnt lgkmcnt(5)
	v_mfma_f32_32x32x16_bf16 v[82:97], v[208:211], v[142:145], v[82:97]
	ds_read_b128 v[232:235], v253 offset:13120
	global_load_dwordx4 v[126:129], v[248:249], off offset:128
	s_waitcnt lgkmcnt(5)
	v_mfma_f32_32x32x16_bf16 v[66:81], v[212:215], v[146:149], v[66:81]
	ds_read_b128 v[236:239], v253 offset:352
	v_add_co_u32_e32 v244, vcc, 0x1a400000, v246
	s_waitcnt lgkmcnt(5)
	v_mfma_f32_32x32x16_bf16 v[82:97], v[216:219], v[146:149], v[82:97]
	ds_read_b128 v[240:243], v253 offset:13152
	s_nop 1
	s_waitcnt lgkmcnt(5)
	v_mfma_f32_32x32x16_bf16 v[66:81], v[220:223], v[154:157], v[66:81]
	v_addc_co_u32_e32 v245, vcc, 0, v247, vcc
	s_waitcnt lgkmcnt(4)
	v_mfma_f32_32x32x16_bf16 v[82:97], v[224:227], v[154:157], v[82:97]
	global_load_dwordx4 v[150:153], v[244:245], off offset:128
	s_waitcnt lgkmcnt(3)
	v_mfma_f32_32x32x16_bf16 v[66:81], v[228:231], v[158:161], v[66:81]
	s_waitcnt lgkmcnt(2)
	v_mfma_f32_32x32x16_bf16 v[82:97], v[232:235], v[158:161], v[82:97]
	s_waitcnt lgkmcnt(1)
	v_mfma_f32_32x32x16_bf16 v[66:81], v[236:239], v[162:165], v[66:81]
	s_waitcnt lgkmcnt(0)
	v_mfma_f32_32x32x16_bf16 v[82:97], v[240:243], v[162:165], v[82:97]
	ds_read_b128 v[196:199], v252 offset:25600
	ds_read_b128 v[200:203], v252 offset:25632
	ds_read_b128 v[204:207], v252 offset:25664
	ds_read_b128 v[208:211], v252 offset:25696
	ds_read_b128 v[212:215], v252 offset:30208
	ds_read_b128 v[216:219], v252 offset:30240
	s_setprio 0
	s_add_i32 s26, s37, 63
	s_cmp_le_i32 s26, s30
	s_cbranch_scc1 .LaF2_1
	v_add_u32_e32 v0, s37, v168
	v_add_u32_e32 v184, 32, v0
	v_cmp_le_i32_e32 vcc, v184, v173
	v_add_u32_e32 v184, 33, v0
	s_nop 3
	v_cndmask_b32_e32 v82, v180, v82, vcc
	v_cmp_lt_i32_e32 vcc, v0, v173
	s_nop 1
	v_cndmask_b32_e32 v67, v180, v67, vcc
	v_cmp_le_i32_e32 vcc, v0, v173
	s_nop 1
	v_cndmask_b32_e32 v66, v180, v66, vcc
	v_cmp_le_i32_e32 vcc, v184, v173
	v_add_u32_e32 v184, 2, v0
	s_nop 0
	v_cndmask_b32_e32 v83, v180, v83, vcc
	v_cmp_le_i32_e32 vcc, v184, v173
	v_add_u32_e32 v184, 34, v0
	s_nop 0
	v_cndmask_b32_e32 v68, v180, v68, vcc
	v_cmp_le_i32_e32 vcc, v184, v173
	v_add_u32_e32 v184, 3, v0
	s_nop 0
	v_cndmask_b32_e32 v84, v180, v84, vcc
	v_cmp_le_i32_e32 vcc, v184, v173
	v_add_u32_e32 v184, 35, v0
	s_nop 0
	v_cndmask_b32_e32 v69, v180, v69, vcc
	v_cmp_le_i32_e32 vcc, v184, v173
	v_add_u32_e32 v184, 4, v0
	s_nop 0
	v_cndmask_b32_e32 v85, v180, v85, vcc
	v_cmp_le_i32_e32 vcc, v184, v173
	v_add_u32_e32 v184, 36, v0
	s_nop 0
	v_cndmask_b32_e32 v70, v180, v70, vcc
	v_cmp_le_i32_e32 vcc, v184, v173
	v_add_u32_e32 v184, 5, v0
	s_nop 0
	v_cndmask_b32_e32 v86, v180, v86, vcc
	v_cmp_le_i32_e32 vcc, v184, v173
	v_add_u32_e32 v184, 37, v0
	s_nop 0
	v_cndmask_b32_e32 v71, v180, v71, vcc
	v_cmp_le_i32_e32 vcc, v184, v173
	v_add_u32_e32 v184, 6, v0
	s_nop 0
	v_cndmask_b32_e32 v87, v180, v87, vcc
	v_cmp_le_i32_e32 vcc, v184, v173
	v_add_u32_e32 v184, 38, v0
	s_nop 0
	v_cndmask_b32_e32 v72, v180, v72, vcc
	v_cmp_le_i32_e32 vcc, v184, v173
	v_add_u32_e32 v184, 7, v0
	s_nop 0
	v_cndmask_b32_e32 v88, v180, v88, vcc
	v_cmp_le_i32_e32 vcc, v184, v173
	v_add_u32_e32 v184, 39, v0
	s_nop 0
	v_cndmask_b32_e32 v73, v180, v73, vcc
	v_cmp_le_i32_e32 vcc, v184, v173
	v_add_u32_e32 v184, 16, v0
	s_nop 0
	v_cndmask_b32_e32 v89, v180, v89, vcc
	v_cmp_le_i32_e32 vcc, v184, v173
	v_add_u32_e32 v184, 48, v0
	s_nop 0
	v_cndmask_b32_e32 v74, v180, v74, vcc
	v_cmp_le_i32_e32 vcc, v184, v173
	v_add_u32_e32 v184, 17, v0
	s_nop 0
	v_cndmask_b32_e32 v90, v180, v90, vcc
	v_cmp_le_i32_e32 vcc, v184, v173
	v_add_u32_e32 v184, 49, v0
	s_nop 0
	v_cndmask_b32_e32 v75, v180, v75, vcc
	v_cmp_le_i32_e32 vcc, v184, v173
	v_add_u32_e32 v184, 18, v0
	s_nop 0
	v_cndmask_b32_e32 v91, v180, v91, vcc
	v_cmp_le_i32_e32 vcc, v184, v173
	v_add_u32_e32 v184, 50, v0
	s_nop 0
	v_cndmask_b32_e32 v76, v180, v76, vcc
	v_cmp_le_i32_e32 vcc, v184, v173
	v_add_u32_e32 v184, 19, v0
	s_nop 0
	v_cndmask_b32_e32 v92, v180, v92, vcc
	v_cmp_le_i32_e32 vcc, v184, v173
	v_add_u32_e32 v184, 51, v0
	s_nop 0
	v_cndmask_b32_e32 v77, v180, v77, vcc
	v_cmp_le_i32_e32 vcc, v184, v173
	v_add_u32_e32 v184, 20, v0
	s_nop 0
	v_cndmask_b32_e32 v93, v180, v93, vcc
	v_cmp_le_i32_e32 vcc, v184, v173
	v_add_u32_e32 v184, 52, v0
	s_nop 0
	v_cndmask_b32_e32 v78, v180, v78, vcc
	v_cmp_le_i32_e32 vcc, v184, v173
	v_add_u32_e32 v184, 21, v0
	s_nop 0
	v_cndmask_b32_e32 v94, v180, v94, vcc
	v_cmp_le_i32_e32 vcc, v184, v173
	v_add_u32_e32 v184, 53, v0
	s_nop 0
	v_cndmask_b32_e32 v79, v180, v79, vcc
	v_cmp_le_i32_e32 vcc, v184, v173
	v_add_u32_e32 v184, 22, v0
	s_nop 0
	v_cndmask_b32_e32 v95, v180, v95, vcc
	v_cmp_le_i32_e32 vcc, v184, v173
	v_add_u32_e32 v184, 54, v0
	s_nop 0
	v_cndmask_b32_e32 v80, v180, v80, vcc
	v_cmp_le_i32_e32 vcc, v184, v173
	v_add_u32_e32 v184, 23, v0
	v_add_u32_e32 v0, 55, v0
	v_cndmask_b32_e32 v96, v180, v96, vcc
	v_cmp_le_i32_e32 vcc, v184, v173
	s_nop 1
	v_cndmask_b32_e32 v81, v180, v81, vcc
	v_cmp_le_i32_e32 vcc, v0, v173
	s_nop 1
	v_cndmask_b32_e32 v97, v180, v97, vcc

.LaF2_2:
	v_sub_f32_e32 v0, v66, v183
	v_exp_f32_e32 v184, v0
	v_sub_f32_e32 v0, v82, v183
	v_exp_f32_e32 v185, v0
	v_sub_f32_e32 v0, v67, v183
	v_exp_f32_e32 v66, v0
	v_sub_f32_e32 v0, v83, v183
	v_exp_f32_e32 v0, v0
	v_add_f32_e32 v67, v184, v185
	v_pk_add_f32 v[82:83], v[66:67], v[0:1]
	v_sub_f32_e32 v67, v68, v183
	v_sub_f32_e32 v68, v84, v183
	v_pk_add_f32 v[82:83], v[82:83], v[82:83] op_sel_hi:[0,1]
	v_exp_f32_e32 v67, v67
	v_exp_f32_e32 v186, v68
	v_sub_f32_e32 v68, v69, v183
	v_sub_f32_e32 v69, v85, v183
	v_exp_f32_e32 v68, v68
	v_exp_f32_e32 v82, v69
	v_add_f32_e32 v69, v67, v186
	v_cvt_pk_bf16_f32 v66, v184, v66
	v_cvt_pk_bf16_f32 v67, v67, v68
	v_pk_add_f32 v[84:85], v[68:69], v[82:83]
	v_sub_f32_e32 v69, v70, v183
	v_sub_f32_e32 v70, v86, v183
	v_pk_add_f32 v[84:85], v[84:85], v[84:85] op_sel_hi:[0,1]
	v_exp_f32_e32 v69, v69
	v_exp_f32_e32 v83, v70
	v_sub_f32_e32 v70, v71, v183
	v_sub_f32_e32 v71, v87, v183
	v_exp_f32_e32 v70, v70
	v_exp_f32_e32 v84, v71
	v_add_f32_e32 v71, v69, v83
	v_cvt_pk_bf16_f32 v68, v69, v70
	v_pk_add_f32 v[86:87], v[70:71], v[84:85]
	v_sub_f32_e32 v71, v72, v183
	v_sub_f32_e32 v72, v88, v183
	v_pk_add_f32 v[86:87], v[86:87], v[86:87] op_sel_hi:[0,1]
	v_exp_f32_e32 v71, v71
	v_exp_f32_e32 v85, v72
	v_sub_f32_e32 v72, v73, v183
	v_sub_f32_e32 v73, v89, v183
	v_exp_f32_e32 v72, v72
	v_exp_f32_e32 v86, v73
	v_add_f32_e32 v73, v71, v85
	v_cvt_pk_bf16_f32 v69, v71, v72
	v_pk_add_f32 v[88:89], v[72:73], v[86:87]
	v_sub_f32_e32 v73, v74, v183
	v_sub_f32_e32 v74, v90, v183
	v_pk_add_f32 v[88:89], v[88:89], v[88:89] op_sel_hi:[0,1]
	v_exp_f32_e32 v73, v73
	v_exp_f32_e32 v87, v74
	v_sub_f32_e32 v74, v75, v183
	v_sub_f32_e32 v75, v91, v183
	v_exp_f32_e32 v74, v74
	v_exp_f32_e32 v88, v75
	v_add_f32_e32 v75, v73, v87
	v_cvt_pk_bf16_f32 v70, v73, v74
	v_pk_add_f32 v[90:91], v[74:75], v[88:89]
	v_sub_f32_e32 v75, v76, v183
	v_sub_f32_e32 v76, v92, v183
	v_pk_add_f32 v[90:91], v[90:91], v[90:91] op_sel_hi:[0,1]
	v_exp_f32_e32 v75, v75
	v_exp_f32_e32 v89, v76
	v_sub_f32_e32 v76, v77, v183
	v_sub_f32_e32 v77, v93, v183
	v_exp_f32_e32 v76, v76
	v_exp_f32_e32 v90, v77
	v_add_f32_e32 v77, v75, v89
	v_cvt_pk_bf16_f32 v71, v75, v76
	v_pk_add_f32 v[92:93], v[76:77], v[90:91]
	v_sub_f32_e32 v77, v78, v183
	v_sub_f32_e32 v78, v94, v183
	v_pk_add_f32 v[92:93], v[92:93], v[92:93] op_sel_hi:[0,1]
	v_exp_f32_e32 v77, v77
	v_exp_f32_e32 v91, v78
	v_sub_f32_e32 v78, v79, v183
	v_sub_f32_e32 v79, v95, v183
	v_exp_f32_e32 v78, v78
	v_exp_f32_e32 v92, v79
	v_add_f32_e32 v79, v77, v91
	v_cvt_pk_bf16_f32 v72, v77, v78
	v_pk_add_f32 v[94:95], v[78:79], v[92:93]
	v_sub_f32_e32 v79, v80, v183
	v_sub_f32_e32 v80, v96, v183
	v_pk_add_f32 v[94:95], v[94:95], v[94:95] op_sel_hi:[0,1]
	v_exp_f32_e32 v79, v79
	v_exp_f32_e32 v93, v80
	v_sub_f32_e32 v80, v81, v183
	v_sub_f32_e32 v81, v97, v183
	v_exp_f32_e32 v80, v80
	v_exp_f32_e32 v94, v81
	v_add_f32_e32 v81, v79, v93
	v_cvt_pk_bf16_f32 v73, v79, v80
	v_cvt_pk_bf16_f32 v74, v185, v0
	v_pk_add_f32 v[96:97], v[80:81], v[94:95]
	v_cvt_pk_bf16_f32 v75, v186, v82
	v_cvt_pk_bf16_f32 v76, v83, v84
	v_cvt_pk_bf16_f32 v77, v85, v86
	v_cvt_pk_bf16_f32 v78, v87, v88
	v_cvt_pk_bf16_f32 v79, v89, v90
	s_nop 0
	v_add_f32_e32 v95, v96, v97
	v_cvt_pk_bf16_f32 v80, v91, v92
	v_cvt_pk_bf16_f32 v81, v93, v94
	s_setprio 1
	v_add_f32_e32 v182, v182, v95
	s_waitcnt lgkmcnt(5)
	v_mfma_f32_32x32x16_bf16 v[50:65], v[196:199], v[66:69], v[50:65]
	ds_read_b128 v[220:223], v252 offset:30272
	s_bitcmp1_b32 s36, 0
	s_waitcnt lgkmcnt(5)
	v_mfma_f32_32x32x16_bf16 v[50:65], v[200:203], v[70:73], v[50:65]
	ds_read_b128 v[224:227], v252 offset:30304
	s_cselect_b32 s99, 0xac00, 0
	s_waitcnt lgkmcnt(5)
	v_mfma_f32_32x32x16_bf16 v[50:65], v[204:207], v[74:77], v[50:65]
	ds_read_b128 v[228:231], v252 offset:34816
	s_add_i32 s99, s99, 0
	s_waitcnt lgkmcnt(5)
	v_mfma_f32_32x32x16_bf16 v[50:65], v[208:211], v[78:81], v[50:65]
	ds_read_b128 v[232:235], v252 offset:34848
	v_add_u32_e32 v250, s99, v170
	s_waitcnt lgkmcnt(5)
	v_mfma_f32_32x32x16_bf16 v[34:49], v[212:215], v[66:69], v[34:49]
	ds_read_b128 v[236:239], v252 offset:34880
	s_waitcnt vmcnt(4)
	s_waitcnt lgkmcnt(5)
	v_mfma_f32_32x32x16_bf16 v[34:49], v[216:219], v[70:73], v[34:49]
	ds_read_b128 v[240:243], v252 offset:34912
	ds_write_b128 v250, v[98:101]
	s_waitcnt lgkmcnt(6)
	v_mfma_f32_32x32x16_bf16 v[34:49], v[220:223], v[74:77], v[34:49]
	ds_read_b128 v[196:199], v252 offset:39424
	s_waitcnt vmcnt(3)
	s_waitcnt lgkmcnt(6)
	v_mfma_f32_32x32x16_bf16 v[34:49], v[224:227], v[78:81], v[34:49]
	ds_read_b128 v[200:203], v252 offset:39456
	ds_write_b128 v250, v[102:105] offset:12800
	s_waitcnt lgkmcnt(7)
	v_mfma_f32_32x32x16_bf16 v[18:33], v[228:231], v[66:69], v[18:33]
	ds_read_b128 v[204:207], v252 offset:39488
	v_add_u32_e32 v250, s99, v172
	s_waitcnt lgkmcnt(7)
	v_mfma_f32_32x32x16_bf16 v[18:33], v[232:235], v[70:73], v[18:33]
	ds_read_b128 v[208:211], v252 offset:39520
	s_waitcnt vmcnt(2)
	s_waitcnt lgkmcnt(7)
	v_mfma_f32_32x32x16_bf16 v[18:33], v[236:239], v[74:77], v[18:33]
	ds_write_b128 v250, v[106:109] offset:256
	s_waitcnt lgkmcnt(7)
	v_mfma_f32_32x32x16_bf16 v[18:33], v[240:243], v[78:81], v[18:33]
	v_add_u32_e32 v250, s99, v169
	s_waitcnt lgkmcnt(5)
	v_mfma_f32_32x32x16_bf16 v[2:17], v[196:199], v[66:69], v[2:17]
	s_waitcnt vmcnt(1)
	s_waitcnt lgkmcnt(4)
	v_mfma_f32_32x32x16_bf16 v[2:17], v[200:203], v[70:73], v[2:17]
	ds_write_b128 v250, v[126:129] offset:25600
	s_waitcnt lgkmcnt(3)
	v_mfma_f32_32x32x16_bf16 v[2:17], v[204:207], v[74:77], v[2:17]
	s_waitcnt vmcnt(0)
	s_waitcnt lgkmcnt(2)
	v_mfma_f32_32x32x16_bf16 v[2:17], v[208:211], v[78:81], v[2:17]
	ds_write_b128 v250, v[150:153] offset:34816
	s_setprio 0
	s_branch .LBB0_1490
